# v24: v23 + gate GEMV in postproc_a2: the 32 LDS weight reads per token are issued together with one wait (register-renamed accumulate chain, same order)
# speedup vs baseline: 1.0080x; 1.0013x over previous
; __device__ __forceinline__ float silu_f(float g) { return g * __builtin_amdgcn_rcpf(1.0f + fast_exp2(-g * LOG2E)); }
; __device__ __forceinline__ u32x2 pack4(const float (&f)[4]) { u32x2 w; w.x = cvtpk(f[0], f[1]); w.y = cvtpk(f[2], f[3]); return w; }
; __device__ __forceinline__ void postproc_a2(const Params& p, LAS unsigned char* lds, int l, int gw, int ngw, int lane) {
;     ...
;         float sg[8];
; #pragma unroll
;         for (int e = 0; e < 4; ++e) { sg[e] = silu_f(a[e]); sg[4 + e] = silu_f(bb[e]); }
;         const float r = kind == 0 ? rsqrtf(s32 * (1.0f / 256) + EPS) : (kind == 1 ? rsqrtf(s16 * (1.0f / 128) + EPS) : rsqrtf(ss * (1.0f / 32) + EPS));
;         scale_rope(a, bb, r, ga, gb, kind == 2, cs32, sn32);
;         if (kind <= 2) { bf16_t* d = dst + (size_t)tok * ts; *(u32x2*)d = pack4(a); *(u32x2*)(d + bo) = pack4(bb); }
;         float acc = gbias;
; #pragma unroll
;         for (int k = 0; k < 64; ++k) acc += __builtin_bit_cast(float, __builtin_amdgcn_readlane(__builtin_bit_cast(int, sg[k & 7]), 52 + (k >> 3))) * gwl[k * 24 + jj];
.LBB0_211:
	s_or_b64 exec, exec, s[0:1]
	s_waitcnt vmcnt(0)
	v_mul_f32_e32 v12, 0xbfb8aa3b, v36
	v_exp_f32_e32 v12, v12
	v_mul_f32_e32 v14, 0xbfb8aa3b, v37
	v_mul_f32_e32 v9, 0xbfb8aa3b, v38
	v_exp_f32_e32 v14, v14
	v_exp_f32_e32 v9, v9
	v_mul_f32_e32 v11, 0xbfb8aa3b, v39
	v_exp_f32_e32 v11, v11
	v_mul_f32_e32 v13, 0xbfb8aa3b, v34
	v_add_f32_e32 v12, 1.0, v12
	v_exp_f32_e32 v13, v13
	v_mul_f32_e32 v15, 0xbfb8aa3b, v35
	v_mul_f32_e32 v8, 0xbfb8aa3b, v40
	v_mul_f32_e32 v10, 0xbfb8aa3b, v41
	v_rcp_f32_e32 v12, v12
	v_add_f32_e32 v14, 1.0, v14
	v_exp_f32_e32 v15, v15
	v_exp_f32_e32 v8, v8
	v_add_f32_e32 v9, 1.0, v9
	v_exp_f32_e32 v10, v10
	v_rcp_f32_e32 v14, v14
	v_rcp_f32_e32 v9, v9
	v_add_f32_e32 v11, 1.0, v11
	v_rcp_f32_e32 v11, v11
	v_add_f32_e32 v13, 1.0, v13
	v_mul_f32_e32 v12, v12, v36
	v_rcp_f32_e32 v13, v13
	v_add_f32_e32 v15, 1.0, v15
	v_add_f32_e32 v8, 1.0, v8
	v_add_f32_e32 v10, 1.0, v10
	v_mul_f32_e32 v14, v14, v37
	v_rcp_f32_e32 v15, v15
	v_readlane_b32 s0, v12, 58
	v_rcp_f32_e32 v8, v8
	v_mul_f32_e32 v9, v9, v38
	v_rcp_f32_e32 v10, v10
	v_writelane_b32 v254, s0, 56
	v_readlane_b32 s0, v14, 58
	v_mul_f32_e32 v11, v11, v39
	v_mul_f32_e32 v13, v13, v34
	v_writelane_b32 v254, s0, 50
	v_readlane_b32 s0, v9, 58
	v_mul_f32_e32 v15, v15, v35
	v_mul_f32_e32 v8, v8, v40
	v_writelane_b32 v254, s0, 46
	v_readlane_b32 s0, v11, 58
	v_mul_f32_e32 v10, v10, v41
	v_readlane_b32 s36, v8, 52
	v_writelane_b32 v254, s0, 58
	v_readlane_b32 s0, v13, 58
	v_readlane_b32 s37, v10, 52
	v_readlane_b32 s34, v12, 52
	v_writelane_b32 v254, s0, 27
	v_readlane_b32 s0, v15, 58
	v_readlane_b32 s35, v14, 52
	v_readlane_b32 s96, v9, 52
	v_readlane_b32 s2, v11, 52
	v_readlane_b32 s20, v13, 52
	v_readlane_b32 s21, v15, 52
	v_readlane_b32 s14, v8, 53
	v_readlane_b32 s15, v10, 53
	v_readlane_b32 s12, v12, 53
	v_readlane_b32 s13, v14, 53
	v_readlane_b32 s18, v9, 53
	v_readlane_b32 s19, v11, 53
	v_readlane_b32 vcc_lo, v13, 53
	v_readlane_b32 vcc_hi, v15, 53
	v_readlane_b32 s76, v8, 54
	v_readlane_b32 s77, v10, 54
	v_readlane_b32 s74, v12, 54
	v_readlane_b32 s75, v14, 54
	v_readlane_b32 s72, v9, 54
	v_readlane_b32 s73, v11, 54
	v_readlane_b32 s67, v13, 54
	v_readlane_b32 s68, v15, 54
	v_readlane_b32 s65, v8, 55
	v_readlane_b32 s66, v10, 55
	v_readlane_b32 s63, v12, 55
	v_readlane_b32 s64, v14, 55
	v_readlane_b32 s61, v9, 55
	v_readlane_b32 s62, v11, 55
	v_readlane_b32 s58, v13, 55
	v_readlane_b32 s59, v15, 55
	v_readlane_b32 s56, v8, 56
	v_readlane_b32 s57, v10, 56
	v_readlane_b32 s54, v12, 56
	v_readlane_b32 s55, v14, 56
	v_readlane_b32 s52, v9, 56
	v_readlane_b32 s53, v11, 56
	v_readlane_b32 s50, v13, 56
	v_readlane_b32 s51, v15, 56
	v_readlane_b32 s48, v8, 57
	v_readlane_b32 s49, v10, 57
	v_readlane_b32 s46, v12, 57
	v_readlane_b32 s47, v14, 57
	v_readlane_b32 s44, v9, 57
	v_readlane_b32 s45, v11, 57
	v_readlane_b32 s42, v13, 57
	v_readlane_b32 s43, v15, 57
	v_readlane_b32 s40, v8, 58
	v_readlane_b32 s41, v10, 58
	v_writelane_b32 v254, s0, 48
	v_readlane_b32 s30, v8, 59
	v_readlane_b32 s31, v10, 59
	v_readlane_b32 s28, v12, 59
	v_readlane_b32 s29, v14, 59
	v_readlane_b32 s26, v9, 59
	v_readlane_b32 s27, v11, 59
	v_readlane_b32 s24, v13, 59
	v_readlane_b32 s25, v15, 59
	s_mov_b64 s[0:1], exec
	v_readlane_b32 s38, v254, 54
	v_readlane_b32 s39, v254, 55
	s_and_b64 s[38:39], s[0:1], s[38:39]
	s_mov_b64 exec, s[38:39]
	s_cbranch_execz .LBB0_198
; __device__ __forceinline__ void postproc_a2(const Params& p, LAS unsigned char* lds, int l, int gw, int ngw, int lane) {
;     ...
;         float acc = gbias;
; #pragma unroll
;         for (int k = 0; k < 64; ++k) acc += __builtin_bit_cast(float, __builtin_amdgcn_readlane(__builtin_bit_cast(int, sg[k & 7]), 52 + (k >> 3))) * gwl[k * 24 + jj];
;         if (lane < 24) GATES[(size_t)tok * 24 + lane] = 1.0f / (1.0f + __expf(-acc));
	ds_read2_b32 v[100:101], v42 offset1:24
	ds_read2_b32 v[102:103], v42 offset0:48 offset1:72
	v_add_u32_e32 v12, 0x1400, v42
	ds_read2_b32 v[104:105], v42 offset0:96 offset1:120
	v_add_u32_e32 v9, 0x200, v42
	ds_read2_b32 v[106:107], v42 offset0:144 offset1:168
	ds_read2_b32 v[108:109], v42 offset0:192 offset1:216
	ds_read2_b32 v[110:111], v9 offset0:112 offset1:136
	v_add_u32_e32 v9, 0x400, v42
	ds_read2_b32 v[112:113], v9 offset0:32 offset1:56
	ds_read2_b32 v[114:115], v9 offset0:80 offset1:104
	ds_read2_b32 v[116:117], v9 offset0:128 offset1:152
	ds_read2_b32 v[118:119], v9 offset0:176 offset1:200
	ds_read2_b32 v[120:121], v9 offset0:224 offset1:248
	v_add_u32_e32 v9, 0x800, v42
	ds_read2_b32 v[122:123], v9 offset0:16 offset1:40
	ds_read2_b32 v[124:125], v9 offset0:64 offset1:88
	ds_read2_b32 v[126:127], v9 offset0:112 offset1:136
	ds_read2_b32 v[128:129], v9 offset0:160 offset1:184
	ds_read2_b32 v[130:131], v9 offset0:208 offset1:232
	v_add_u32_e32 v9, 0xc00, v42
	ds_read2_b32 v[132:133], v9 offset1:24
	ds_read2_b32 v[134:135], v9 offset0:48 offset1:72
	ds_read2_b32 v[136:137], v9 offset0:96 offset1:120
	ds_read2_b32 v[138:139], v9 offset0:144 offset1:168
	ds_read2_b32 v[140:141], v9 offset0:192 offset1:216
	v_add_u32_e32 v9, 0xe00, v42
	ds_read2_b32 v[142:143], v9 offset0:112 offset1:136
	v_add_u32_e32 v9, 0x1000, v42
	ds_read2_b32 v[144:145], v9 offset0:32 offset1:56
	ds_read2_b32 v[146:147], v9 offset0:80 offset1:104
	ds_read2_b32 v[148:149], v9 offset0:128 offset1:152
	ds_read2_b32 v[150:151], v9 offset0:176 offset1:200
	ds_read2_b32 v[152:153], v9 offset0:224 offset1:248
	ds_read2_b32 v[154:155], v12 offset0:16 offset1:40
	ds_read2_b32 v[156:157], v12 offset0:64 offset1:88
	ds_read2_b32 v[158:159], v12 offset0:112 offset1:136
	ds_read2_b32 v[160:161], v12 offset0:160 offset1:184
	ds_read2_b32 v[162:163], v12 offset0:208 offset1:232
	s_waitcnt lgkmcnt(0)
	v_fma_f32 v8, s36, v100, v21
	v_fmac_f32_e32 v8, s37, v101
	v_fmac_f32_e32 v8, s34, v102
	v_fmac_f32_e32 v8, s35, v103
	v_fmac_f32_e32 v8, s96, v104
	v_fmac_f32_e32 v8, s2, v105
	v_readlane_b32 s2, v254, 56
	v_fmac_f32_e32 v8, s20, v106
	v_fmac_f32_e32 v8, s21, v107
	v_fmac_f32_e32 v8, s14, v108
	v_fmac_f32_e32 v8, s15, v109
	v_fmac_f32_e32 v8, s12, v110
	v_fmac_f32_e32 v8, s13, v111
	v_fmac_f32_e32 v8, s18, v112
	v_fmac_f32_e32 v8, s19, v113
	v_fmac_f32_e32 v8, vcc_lo, v114
	v_fmac_f32_e32 v8, vcc_hi, v115
	v_fmac_f32_e32 v8, s76, v116
	v_fmac_f32_e32 v8, s77, v117
	v_fmac_f32_e32 v8, s74, v118
	v_fmac_f32_e32 v8, s75, v119
	v_fmac_f32_e32 v8, s72, v120
	v_fmac_f32_e32 v8, s73, v121
	v_fmac_f32_e32 v8, s67, v122
	v_fmac_f32_e32 v8, s68, v123
	v_fmac_f32_e32 v8, s65, v124
	v_fmac_f32_e32 v8, s66, v125
	v_fmac_f32_e32 v8, s63, v126
	v_fmac_f32_e32 v8, s64, v127
	v_fmac_f32_e32 v8, s61, v128
	v_fmac_f32_e32 v8, s62, v129
	v_fmac_f32_e32 v8, s58, v130
	v_fmac_f32_e32 v8, s59, v131
	v_fmac_f32_e32 v8, s56, v132
	v_fmac_f32_e32 v8, s57, v133
	v_fmac_f32_e32 v8, s54, v134
	v_fmac_f32_e32 v8, s55, v135
	v_fmac_f32_e32 v8, s52, v136
	v_fmac_f32_e32 v8, s53, v137
	v_fmac_f32_e32 v8, s50, v138
	v_fmac_f32_e32 v8, s51, v139
	v_fmac_f32_e32 v8, s48, v140
	v_fmac_f32_e32 v8, s49, v141
	v_fmac_f32_e32 v8, s46, v142
	v_fmac_f32_e32 v8, s47, v143
	v_fmac_f32_e32 v8, s44, v144
	v_fmac_f32_e32 v8, s45, v145
	v_fmac_f32_e32 v8, s42, v146
	v_fmac_f32_e32 v8, s43, v147
	v_fmac_f32_e32 v8, s40, v148
	v_fmac_f32_e32 v8, s41, v149
	v_fmac_f32_e32 v8, s2, v150
	v_readlane_b32 s2, v254, 50
	s_nop 1
	v_fmac_f32_e32 v8, s2, v151
	v_readlane_b32 s2, v254, 46
	s_nop 0
	s_nop 0
	v_fmac_f32_e32 v8, s2, v152
	v_readlane_b32 s2, v254, 58
	s_nop 1
	v_fmac_f32_e32 v8, s2, v153
	v_readlane_b32 s2, v254, 27
	s_nop 0
	s_nop 0
	v_fmac_f32_e32 v8, s2, v154
	v_readlane_b32 s2, v254, 48
	s_nop 1
	v_fmac_f32_e32 v8, s2, v155
	v_pk_mul_f32 v[10:11], v[156:157], s[30:31]
	s_nop 0
	v_add_f32_e32 v8, v8, v10
	v_add_f32_e32 v10, v8, v11
	v_pk_mul_f32 v[8:9], v[158:159], s[28:29]
	s_nop 0
	v_add_f32_e32 v8, v10, v8
	v_add_f32_e32 v10, v8, v9
	v_pk_mul_f32 v[8:9], v[160:161], s[26:27]
	s_nop 0
	v_add_f32_e32 v8, v10, v8
	v_add_f32_e32 v10, v8, v9
	v_pk_mul_f32 v[8:9], v[162:163], s[24:25]
	s_nop 0
	v_add_f32_e32 v8, v10, v8
	v_add_f32_e32 v8, v8, v9
	v_mul_f32_e32 v8, 0xbfb8aa3b, v8
	v_exp_f32_e32 v8, v8
	s_nop 0
	v_add_f32_e32 v8, 1.0, v8
	v_div_scale_f32 v9, s[12:13], v8, v8, 1.0
	v_rcp_f32_e32 v10, v9
	s_nop 0
	v_fma_f32 v11, -v9, v10, 1.0
	v_fmac_f32_e32 v10, v11, v10
	v_div_scale_f32 v11, vcc, 1.0, v8, 1.0
	v_mul_f32_e32 v12, v11, v10
	v_fma_f32 v13, -v9, v12, v11
	v_fmac_f32_e32 v12, v13, v10
	v_fma_f32 v9, -v9, v12, v11
	v_div_fmas_f32 v9, v9, v10, v12
	v_div_fixup_f32 v10, v9, v8, 1.0
	v_lshl_add_u64 v[8:9], s[6:7], 0, v[22:23]
	global_store_dword v[8:9], v10, off
	s_branch .LBB0_198
